# DeltaNet chain step: packed f32 mul/add beside MFMAs split into scalar pairs (bit-identical)
# speedup vs baseline: 1.0091x; 1.0032x over previous
; #define MFMA32(a, b, c) __builtin_amdgcn_mfma_f32_32x32x16_bf16((a), (b), (c), 0, 0, 0)
; DI void chain_step(f32x16 (&Sacc)[4], u32x4 (&uv)[4], const LAS unsigned char* buf, float gl, const bf16* uv_next, bf16* oraw, int r, int h2) {
;     ...
;         for (int j = 0; j < 8; ++j) { const unsigned w = uv[2 * ti + (j >> 2)][j & 3]; U[ti][2 * j] = bflo(w) - U[ti][2 * j]; U[ti][2 * j + 1] = bfhi(w) - U[ti][2 * j + 1]; }
;     if (uv_next) {
; #pragma unroll
;         for (int q = 0; q < 4; ++q) uv[q] = *(const u32x4*)(uv_next + (size_t)((q >> 1) * 64) * 16 + (q & 1) * 8); }
;     bf16x8 Uf[4];
; #pragma unroll
;     for (int k2 = 0; k2 < 4; ++k2) Uf[k2] = pack8(U[k2 >> 1], k2 & 1);
;     bf16x8 fp[4];
; #pragma unroll
;     for (int k2 = 0; k2 < 4; ++k2) fp[k2] = FR(PMl, TLD, 0, k2);
;     __builtin_amdgcn_sched_barrier(0);
; #pragma unroll
;     for (int d = 0; d < 2; ++d) {
; #pragma unroll
;         for (int i = 0; i < 16; ++i) Sacc[d][i] *= gl;
; #pragma unroll
;         for (int k2 = 0; k2 < 4; ++k2) Sacc[d] = MFMA32(fk[d][k2], Uf[k2], Sacc[d]); }
; #pragma unroll
;     for (int d = 0; d < 2; ++d)
; #pragma unroll
;         for (int k2 = 0; k2 < 4; ++k2) fk[d][k2] = FR(KGTl, TLD, 2 + d, k2);
;     __builtin_amdgcn_sched_barrier(0);
; #pragma unroll
;     for (int k2 = 0; k2 < 4; ++k2) accO[0] = MFMA32(fp[k2], Uf[k2], accO[0]);
; #pragma unroll
;     for (int k2 = 0; k2 < 4; ++k2) fp[k2] = FR(PMl, TLD, 1, k2);
;     __builtin_amdgcn_sched_barrier(0);
; #pragma unroll
;     for (int d = 0; d < 2; ++d) {
; #pragma unroll
;         for (int i = 0; i < 16; ++i) Sacc[2 + d][i] *= gl;
; #pragma unroll
;         for (int k2 = 0; k2 < 4; ++k2) Sacc[2 + d] = MFMA32(fk[d][k2], Uf[k2], Sacc[2 + d]); }
; #pragma unroll
;     for (int k2 = 0; k2 < 4; ++k2) accO[1] = MFMA32(fp[k2], Uf[k2], accO[1]);
.LBB0_1773:
	s_waitcnt vmcnt(5)
	v_lshlrev_b32_e32 v224, 16, v161
	v_and_b32_e32 v225, 0xffff0000, v161
	v_sub_f32_e32 v224, v224, v128
	v_sub_f32_e32 v225, v225, v129
	v_lshlrev_b32_e32 v128, 16, v160
	v_and_b32_e32 v129, 0xffff0000, v160
	v_sub_f32_e32 v160, v128, v126
	v_sub_f32_e32 v161, v129, v127
	v_lshlrev_b32_e32 v126, 16, v159
	v_and_b32_e32 v127, 0xffff0000, v159
	v_sub_f32_e32 v226, v126, v124
	v_sub_f32_e32 v227, v127, v125
	v_lshlrev_b32_e32 v124, 16, v158
	v_and_b32_e32 v125, 0xffff0000, v158
	v_sub_f32_e32 v158, v124, v122
	v_sub_f32_e32 v159, v125, v123
	s_waitcnt vmcnt(4)
	v_lshlrev_b32_e32 v122, 16, v157
	v_and_b32_e32 v123, 0xffff0000, v157
	v_sub_f32_e32 v120, v122, v120
	v_sub_f32_e32 v121, v123, v121
	v_lshlrev_b32_e32 v122, 16, v156
	v_and_b32_e32 v123, 0xffff0000, v156
	v_sub_f32_e32 v118, v122, v118
	v_sub_f32_e32 v119, v123, v119
	v_lshlrev_b32_e32 v122, 16, v155
	v_and_b32_e32 v123, 0xffff0000, v155
	v_sub_f32_e32 v116, v122, v116
	v_sub_f32_e32 v117, v123, v117
	v_lshlrev_b32_e32 v122, 16, v154
	v_and_b32_e32 v123, 0xffff0000, v154
	v_sub_f32_e32 v114, v122, v114
	v_sub_f32_e32 v115, v123, v115
	v_lshlrev_b32_e32 v122, 16, v150
	v_and_b32_e32 v123, 0xffff0000, v150
	v_sub_f32_e32 v98, v122, v98
	v_sub_f32_e32 v99, v123, v99
	v_lshlrev_b32_e32 v122, 16, v151
	v_and_b32_e32 v123, 0xffff0000, v151
	v_sub_f32_e32 v100, v122, v100
	v_sub_f32_e32 v101, v123, v101
	v_lshlrev_b32_e32 v122, 16, v152
	v_and_b32_e32 v123, 0xffff0000, v152
	v_sub_f32_e32 v102, v122, v102
	v_sub_f32_e32 v103, v123, v103
	v_lshlrev_b32_e32 v122, 16, v153
	v_and_b32_e32 v123, 0xffff0000, v153
	v_sub_f32_e32 v104, v122, v104
	v_sub_f32_e32 v105, v123, v105
	v_lshlrev_b32_e32 v122, 16, v146
	v_and_b32_e32 v123, 0xffff0000, v146
	v_sub_f32_e32 v106, v122, v106
	v_sub_f32_e32 v107, v123, v107
	v_lshlrev_b32_e32 v122, 16, v147
	v_and_b32_e32 v123, 0xffff0000, v147
	v_sub_f32_e32 v108, v122, v108
	v_sub_f32_e32 v109, v123, v109
	v_lshlrev_b32_e32 v122, 16, v148
	v_and_b32_e32 v123, 0xffff0000, v148
	v_sub_f32_e32 v122, v122, v110
	v_sub_f32_e32 v123, v123, v111
	v_lshlrev_b32_e32 v110, 16, v149
	v_and_b32_e32 v111, 0xffff0000, v149
	v_sub_f32_e32 v124, v110, v112
	v_sub_f32_e32 v125, v111, v113
	v_cvt_pk_bf16_f32 v112, v102, v103
	v_cvt_pk_bf16_f32 v113, v104, v105
	v_cvt_pk_bf16_f32 v106, v106, v107
	v_cvt_pk_bf16_f32 v107, v108, v109
	v_cvt_pk_bf16_f32 v108, v122, v123
	v_cvt_pk_bf16_f32 v109, v124, v125
	v_cvt_pk_bf16_f32 v102, v114, v115
	v_cvt_pk_bf16_f32 v103, v116, v117
	v_cvt_pk_bf16_f32 v104, v118, v119
	v_cvt_pk_bf16_f32 v105, v120, v121
	ds_read_b128 v[114:117], v223
	ds_read_b128 v[118:121], v223 offset:32
	ds_read_b128 v[122:125], v223 offset:64
	ds_read_b128 v[126:129], v223 offset:96
	v_lshl_add_u64 v[204:205], s[42:43], 1, v[200:201]
	v_cvt_pk_bf16_f32 v110, v98, v99
	v_cvt_pk_bf16_f32 v111, v100, v101
	v_cvt_pk_bf16_f32 v98, v158, v159
	v_cvt_pk_bf16_f32 v99, v226, v227
	v_cvt_pk_bf16_f32 v100, v160, v161
	v_cvt_pk_bf16_f32 v101, v224, v225
	v_mul_f32_e32 v64, v196, v64
	v_mul_f32_e32 v65, v196, v65
	v_mul_f32_e32 v62, v196, v62
	v_mul_f32_e32 v63, v196, v63
	v_mul_f32_e32 v60, v196, v60
	v_mul_f32_e32 v61, v196, v61
	v_mul_f32_e32 v58, v196, v58
	v_mul_f32_e32 v59, v196, v59
	v_mul_f32_e32 v56, v196, v56
	v_mul_f32_e32 v57, v196, v57
	v_mul_f32_e32 v54, v196, v54
	v_mul_f32_e32 v55, v196, v55
	v_mul_f32_e32 v52, v196, v52
	v_mul_f32_e32 v53, v196, v53
	v_mul_f32_e32 v50, v196, v50
	v_mul_f32_e32 v51, v196, v51
	v_mul_f32_e32 v32, v196, v32
	v_mul_f32_e32 v33, v196, v33
	v_mul_f32_e32 v30, v196, v30
	v_mul_f32_e32 v31, v196, v31
	s_waitcnt lgkmcnt(7)
	v_mfma_f32_32x32x16_bf16 v[50:65], v[174:177], v[110:113], v[50:65]
	v_mul_f32_e64 v28, v196, v28
	v_mul_f32_e64 v29, v196, v29
	v_mul_f32_e64 v26, v196, v26
	v_mul_f32_e64 v27, v196, v27
	v_mul_f32_e64 v24, v196, v24
	v_mul_f32_e64 v25, v196, v25
	v_mul_f32_e32 v22, v196, v22
	v_mul_f32_e32 v23, v196, v23
	v_mul_f32_e32 v20, v196, v20
	v_mul_f32_e32 v21, v196, v21
	v_mul_f32_e32 v18, v196, v18
	v_mul_f32_e32 v19, v196, v19
	s_waitcnt lgkmcnt(6)
	v_mfma_f32_32x32x16_bf16 v[50:65], v[170:173], v[106:109], v[50:65]
	v_mfma_f32_32x32x16_bf16 v[18:33], v[190:193], v[110:113], v[18:33]
	v_mfma_f32_32x32x16_bf16 v[18:33], v[186:189], v[106:109], v[18:33]
	s_waitcnt lgkmcnt(5)
	v_mfma_f32_32x32x16_bf16 v[50:65], v[162:165], v[102:105], v[50:65]
	v_mfma_f32_32x32x16_bf16 v[18:33], v[182:185], v[102:105], v[18:33]
	s_waitcnt lgkmcnt(4)
	v_mfma_f32_32x32x16_bf16 v[50:65], v[166:169], v[98:101], v[50:65]
	ds_read_b128 v[146:149], v222 offset:9216
	ds_read_b128 v[150:153], v222 offset:9248
	ds_read_b128 v[154:157], v222 offset:9280
	ds_read_b128 v[158:161], v222 offset:9312
	ds_read_b128 v[162:165], v222 offset:13824
	ds_read_b128 v[166:169], v222 offset:13856
	ds_read_b128 v[170:173], v222 offset:13888
	ds_read_b128 v[174:177], v222 offset:13920
	v_mfma_f32_32x32x16_bf16 v[18:33], v[178:181], v[98:101], v[18:33]
	s_waitcnt lgkmcnt(11)
	v_mfma_f32_32x32x16_bf16 v[82:97], v[114:117], v[110:113], v[82:97]
	s_waitcnt lgkmcnt(10)
	v_mfma_f32_32x32x16_bf16 v[82:97], v[118:121], v[106:109], v[82:97]
	s_waitcnt lgkmcnt(9)
	v_mfma_f32_32x32x16_bf16 v[82:97], v[122:125], v[102:105], v[82:97]
	s_waitcnt lgkmcnt(8)
	v_mfma_f32_32x32x16_bf16 v[82:97], v[126:129], v[98:101], v[82:97]
	ds_read_b128 v[114:117], v223 offset:4608
	ds_read_b128 v[118:121], v223 offset:4640
	ds_read_b128 v[122:125], v223 offset:4672
	ds_read_b128 v[126:129], v223 offset:4704
	s_waitcnt lgkmcnt(3)
; DI unsigned pk2(float lo, float hi) { f32x2 v = {lo, hi}; return __builtin_bit_cast(unsigned, __builtin_convertvector(v, bf16v2)); }
; #define MFMA32(a, b, c) __builtin_amdgcn_mfma_f32_32x32x16_bf16((a), (b), (c), 0, 0, 0)
; DI void chain_step(f32x16 (&Sacc)[4], u32x4 (&uv)[4], const LAS unsigned char* buf, float gl, const bf16* uv_next, bf16* oraw, int r, int h2) {
;     ...
;     fw[0][0] = FR(WKl, QLD, 0, 0); fw[0][1] = FR(WKl, QLD, 1, 0); fq[0][0] = FR(QGl, QLD, 0, 0); fq[0][1] = FR(QGl, QLD, 1, 0);
; #pragma unroll
;     for (int kk = 0; kk < 8; ++kk) { const int cb = kk & 1, nb = cb ^ 1;
;         if (kk < 7) { fw[nb][0] = FR(WKl, QLD, 0, kk + 1); fw[nb][1] = FR(WKl, QLD, 1, kk + 1); fq[nb][0] = FR(QGl, QLD, 0, kk + 1); fq[nb][1] = FR(QGl, QLD, 1, kk + 1); }
;         const bf16x8 sf = pack8(Sacc[kk >> 1], kk & 1);
;         __builtin_amdgcn_sched_barrier(0);
;         U[0] = MFMA32(fw[cb][0], sf, U[0]); U[1] = MFMA32(fw[cb][1], sf, U[1]); accO[0] = MFMA32(fq[cb][0], sf, accO[0]); accO[1] = MFMA32(fq[cb][1], sf, accO[1]);
;         __builtin_amdgcn_sched_barrier(0); }
;     ...
;     for (int k2 = 0; k2 < 4; ++k2) accO[0] = MFMA32(fp[k2], Uf[k2], accO[0]);
; #pragma unroll
;     for (int k2 = 0; k2 < 4; ++k2) fp[k2] = FR(PMl, TLD, 1, k2);
;     __builtin_amdgcn_sched_barrier(0);
; #pragma unroll
;     for (int d = 0; d < 2; ++d) {
; #pragma unroll
;         for (int i = 0; i < 16; ++i) Sacc[2 + d][i] *= gl;
; #pragma unroll
;         for (int k2 = 0; k2 < 4; ++k2) Sacc[2 + d] = MFMA32(fk[d][k2], Uf[k2], Sacc[2 + d]); }
; #pragma unroll
;     for (int k2 = 0; k2 < 4; ++k2) accO[1] = MFMA32(fp[k2], Uf[k2], accO[1]);
; #pragma unroll
;     for (int ti = 0; ti < 2; ++ti) { u32x4 w0, w1;
; #pragma unroll
;         for (int j = 0; j < 4; ++j) { w0[j] = pk2(accO[ti][2 * j], accO[ti][2 * j + 1]); w1[j] = pk2(accO[ti][8 + 2 * j], accO[ti][8 + 2 * j + 1]); }
;         *(u32x4*)(oraw + (size_t)(ti * 64) * 16) = w0; *(u32x4*)(oraw + (size_t)(ti * 64) * 16 + 8) = w1; }
	v_mfma_f32_32x32x16_bf16 v[66:81], v[114:117], v[110:113], v[66:81]
	v_mul_f32_e64 v48, v196, v48
	v_mul_f32_e64 v49, v196, v49
	v_mul_f32_e64 v46, v196, v46
	v_mul_f32_e64 v47, v196, v47
	v_mul_f32_e64 v44, v196, v44
	v_mul_f32_e64 v45, v196, v45
	v_mul_f32_e32 v42, v196, v42
	v_mul_f32_e32 v43, v196, v43
	v_mul_f32_e32 v40, v196, v40
	v_mul_f32_e32 v41, v196, v41
	v_mul_f32_e32 v38, v196, v38
	v_mul_f32_e32 v39, v196, v39
	v_mul_f32_e32 v36, v196, v36
	v_mul_f32_e32 v37, v196, v37
	v_mul_f32_e32 v34, v196, v34
	v_mul_f32_e32 v35, v196, v35
	v_mul_f32_e32 v16, v196, v16
	v_mul_f32_e32 v17, v196, v17
	v_mul_f32_e32 v14, v196, v14
	v_mul_f32_e32 v15, v196, v15
	v_mul_f32_e32 v12, v196, v12
	v_mul_f32_e32 v13, v196, v13
	v_mul_f32_e32 v10, v196, v10
	v_mul_f32_e32 v11, v196, v11
	v_mul_f32_e32 v8, v196, v8
	v_mul_f32_e32 v9, v196, v9
	v_mul_f32_e32 v6, v196, v6
	v_mul_f32_e32 v7, v196, v7
	v_mul_f32_e32 v4, v196, v4
	v_mul_f32_e32 v5, v196, v5
	v_mul_f32_e32 v2, v196, v2
	v_mul_f32_e32 v3, v196, v3
	v_mfma_f32_32x32x16_bf16 v[34:49], v[146:149], v[110:113], v[34:49]
	v_cvt_pk_bf16_f32 v82, v82, v83
	v_cvt_pk_bf16_f32 v83, v84, v85
	v_cvt_pk_bf16_f32 v84, v86, v87
	v_cvt_pk_bf16_f32 v85, v88, v89
	v_cvt_pk_bf16_f32 v90, v90, v91
	v_cvt_pk_bf16_f32 v91, v92, v93
	v_cvt_pk_bf16_f32 v92, v94, v95
	v_mfma_f32_32x32x16_bf16 v[2:17], v[162:165], v[110:113], v[2:17]
	v_cvt_pk_bf16_f32 v93, v96, v97
	global_store_dwordx4 v[204:205], v[82:85], off
	global_store_dwordx4 v[204:205], v[90:93], off offset:16
	s_add_i32 s10, s10, 16
	s_add_u32 s38, s38, 64
	s_addc_u32 s39, s39, 0
	s_cmp_gt_u32 s80, 61
	s_mov_b32 s40, s56
	s_waitcnt lgkmcnt(2)
	v_mfma_f32_32x32x16_bf16 v[66:81], v[118:121], v[106:109], v[66:81]
	v_mfma_f32_32x32x16_bf16 v[34:49], v[150:153], v[106:109], v[34:49]
	v_mfma_f32_32x32x16_bf16 v[2:17], v[166:169], v[106:109], v[2:17]
	s_waitcnt lgkmcnt(1)
	v_mfma_f32_32x32x16_bf16 v[66:81], v[122:125], v[102:105], v[66:81]
	v_mfma_f32_32x32x16_bf16 v[34:49], v[154:157], v[102:105], v[34:49]
	v_mfma_f32_32x32x16_bf16 v[2:17], v[170:173], v[102:105], v[2:17]
	s_waitcnt lgkmcnt(0)
	v_mfma_f32_32x32x16_bf16 v[66:81], v[126:129], v[98:101], v[66:81]
	v_mfma_f32_32x32x16_bf16 v[34:49], v[158:161], v[98:101], v[34:49]
	s_nop 10
	v_cvt_pk_bf16_f32 v66, v66, v67
	v_cvt_pk_bf16_f32 v67, v68, v69
	v_cvt_pk_bf16_f32 v68, v70, v71
	v_cvt_pk_bf16_f32 v69, v72, v73
	v_cvt_pk_bf16_f32 v74, v74, v75
	v_cvt_pk_bf16_f32 v75, v76, v77
	v_cvt_pk_bf16_f32 v76, v78, v79
	v_mfma_f32_32x32x16_bf16 v[2:17], v[174:177], v[98:101], v[2:17]
	v_cvt_pk_bf16_f32 v77, v80, v81
	global_store_dwordx4 v[204:205], v[66:69], off offset:2048
	global_store_dwordx4 v[204:205], v[74:77], off offset:2064
	s_waitcnt lgkmcnt(0)
	s_barrier
	s_cbranch_scc1 .LBB0_1783
.LBB0_1774:
	s_add_i32 s80, s80, 2
	s_lshl_b64 s[42:43], s[10:11], 2
	s_add_u32 s42, s53, s42
	s_addc_u32 s43, s54, s43
	global_load_dword v196, v197, s[42:43]
	s_waitcnt vmcnt(15)
	ds_read_b128 v[66:69], v217
	ds_read_b128 v[146:149], v217 offset:32
	s_waitcnt vmcnt(13)
	ds_read_b128 v[70:73], v217 offset:8704
	ds_read_b128 v[150:153], v217 offset:8736
	ds_read_b128 v[74:77], v217 offset:17408
	ds_read_b128 v[156:159], v217 offset:17440
	s_waitcnt vmcnt(12)
	ds_read_b128 v[78:81], v217 offset:26112
	ds_read_b128 v[164:167], v217 offset:26144
	s_lshl_b64 s[42:43], s[10:11], 14
	v_lshl_add_u64 v[154:155], v[198:199], 0, s[42:43]
	s_mov_b32 s41, s11
	v_lshl_add_u64 v[162:163], s[40:41], 1, v[200:201]
	v_cvt_pk_bf16_f32 v168, v18, v19
	v_cvt_pk_bf16_f32 v169, v20, v21
	v_cvt_pk_bf16_f32 v170, v22, v23
	v_cvt_pk_bf16_f32 v171, v24, v25
	s_waitcnt vmcnt(6) lgkmcnt(7)
	s_nop 0
	v_mfma_f32_32x32x16_bf16 v[98:113], v[66:69], v[168:171], 0
	s_waitcnt lgkmcnt(5)
	v_mfma_f32_32x32x16_bf16 v[114:129], v[70:73], v[168:171], 0
	s_waitcnt lgkmcnt(3)
	v_mfma_f32_32x32x16_bf16 v[82:97], v[74:77], v[168:171], 0
	s_waitcnt lgkmcnt(1)
	v_mfma_f32_32x32x16_bf16 v[66:81], v[78:81], v[168:171], 0
	ds_read_b128 v[168:171], v217 offset:64
	ds_read_b128 v[172:175], v217 offset:8768
	ds_read_b128 v[176:179], v217 offset:17472
	ds_read_b128 v[180:183], v217 offset:26176
	v_cvt_pk_bf16_f32 v184, v26, v27
	v_cvt_pk_bf16_f32 v185, v28, v29
	v_cvt_pk_bf16_f32 v186, v30, v31
	v_cvt_pk_bf16_f32 v187, v32, v33
	s_nop 1
	v_mfma_f32_32x32x16_bf16 v[98:113], v[146:149], v[184:187], v[98:113]
	v_mfma_f32_32x32x16_bf16 v[114:129], v[150:153], v[184:187], v[114:129]
	v_mfma_f32_32x32x16_bf16 v[82:97], v[156:159], v[184:187], v[82:97]
	s_waitcnt lgkmcnt(4)
	v_mfma_f32_32x32x16_bf16 v[66:81], v[164:167], v[184:187], v[66:81]
	ds_read_b128 v[146:149], v217 offset:96
	ds_read_b128 v[150:153], v217 offset:8800
	ds_read_b128 v[156:159], v217 offset:17504
	ds_read_b128 v[164:167], v217 offset:26208
	v_cvt_pk_bf16_f32 v184, v50, v51
	v_cvt_pk_bf16_f32 v185, v52, v53
	v_cvt_pk_bf16_f32 v186, v54, v55
	v_cvt_pk_bf16_f32 v187, v56, v57
	s_waitcnt lgkmcnt(7)
	s_nop 0
	v_mfma_f32_32x32x16_bf16 v[98:113], v[168:171], v[184:187], v[98:113]
	s_waitcnt lgkmcnt(6)
	v_mfma_f32_32x32x16_bf16 v[114:129], v[172:175], v[184:187], v[114:129]
	s_waitcnt lgkmcnt(5)
	v_mfma_f32_32x32x16_bf16 v[82:97], v[176:179], v[184:187], v[82:97]
	s_waitcnt lgkmcnt(4)
	v_mfma_f32_32x32x16_bf16 v[66:81], v[180:183], v[184:187], v[66:81]
	ds_read_b128 v[168:171], v217 offset:128
	ds_read_b128 v[172:175], v217 offset:8832
	ds_read_b128 v[176:179], v217 offset:17536
	ds_read_b128 v[180:183], v217 offset:26240
	v_cvt_pk_bf16_f32 v184, v58, v59
	v_cvt_pk_bf16_f32 v185, v60, v61
	v_cvt_pk_bf16_f32 v186, v62, v63
	v_cvt_pk_bf16_f32 v187, v64, v65
	s_waitcnt lgkmcnt(7)
; #define MFMA32(a, b, c) __builtin_amdgcn_mfma_f32_32x32x16_bf16((a), (b), (c), 0, 0, 0)
; DI void chain_step(f32x16 (&Sacc)[4], u32x4 (&uv)[4], const LAS unsigned char* buf, float gl, const bf16* uv_next, bf16* oraw, int r, int h2) {
;     ...
;     for (int kk = 0; kk < 8; ++kk) { const int cb = kk & 1, nb = cb ^ 1;
;         if (kk < 7) { fw[nb][0] = FR(WKl, QLD, 0, kk + 1); fw[nb][1] = FR(WKl, QLD, 1, kk + 1); fq[nb][0] = FR(QGl, QLD, 0, kk + 1); fq[nb][1] = FR(QGl, QLD, 1, kk + 1); }
;         const bf16x8 sf = pack8(Sacc[kk >> 1], kk & 1);
;         __builtin_amdgcn_sched_barrier(0);
;         U[0] = MFMA32(fw[cb][0], sf, U[0]); U[1] = MFMA32(fw[cb][1], sf, U[1]); accO[0] = MFMA32(fq[cb][0], sf, accO[0]); accO[1] = MFMA32(fq[cb][1], sf, accO[1]);
;         __builtin_amdgcn_sched_barrier(0); }
;     bf16x8 fk[2][4];
; #pragma unroll
;     for (int d = 0; d < 2; ++d)
; #pragma unroll
;         for (int k2 = 0; k2 < 4; ++k2) fk[d][k2] = FR(KGTl, TLD, d, k2);
;     __builtin_amdgcn_sched_barrier(0);
; #pragma unroll
;     for (int ti = 0; ti < 2; ++ti)
; #pragma unroll
;         for (int j = 0; j < 8; ++j) { const unsigned w = uv[2 * ti + (j >> 2)][j & 3]; U[ti][2 * j] = bflo(w) - U[ti][2 * j]; U[ti][2 * j + 1] = bfhi(w) - U[ti][2 * j + 1]; }
;     if (uv_next) {
; #pragma unroll
;         for (int q = 0; q < 4; ++q) uv[q] = *(const u32x4*)(uv_next + (size_t)((q >> 1) * 64) * 16 + (q & 1) * 8); }
;     bf16x8 Uf[4];
; #pragma unroll
;     for (int k2 = 0; k2 < 4; ++k2) Uf[k2] = pack8(U[k2 >> 1], k2 & 1);
;     bf16x8 fp[4];
; #pragma unroll
;     for (int k2 = 0; k2 < 4; ++k2) fp[k2] = FR(PMl, TLD, 0, k2);
	s_nop 0
	v_mfma_f32_32x32x16_bf16 v[98:113], v[146:149], v[184:187], v[98:113]
	s_waitcnt lgkmcnt(6)
	v_mfma_f32_32x32x16_bf16 v[114:129], v[150:153], v[184:187], v[114:129]
	s_waitcnt lgkmcnt(5)
	v_mfma_f32_32x32x16_bf16 v[82:97], v[156:159], v[184:187], v[82:97]
	s_waitcnt lgkmcnt(4)
	v_mfma_f32_32x32x16_bf16 v[66:81], v[164:167], v[184:187], v[66:81]
	ds_read_b128 v[146:149], v217 offset:160
	ds_read_b128 v[150:153], v217 offset:8864
	ds_read_b128 v[156:159], v217 offset:17568
	ds_read_b128 v[164:167], v217 offset:26272
	v_cvt_pk_bf16_f32 v184, v34, v35
	v_cvt_pk_bf16_f32 v185, v36, v37
	v_cvt_pk_bf16_f32 v186, v38, v39
	v_cvt_pk_bf16_f32 v187, v40, v41
	s_waitcnt lgkmcnt(7)
	s_nop 0
	v_mfma_f32_32x32x16_bf16 v[98:113], v[168:171], v[184:187], v[98:113]
	s_waitcnt lgkmcnt(6)
	v_mfma_f32_32x32x16_bf16 v[114:129], v[172:175], v[184:187], v[114:129]
	s_waitcnt lgkmcnt(5)
	v_mfma_f32_32x32x16_bf16 v[82:97], v[176:179], v[184:187], v[82:97]
	s_waitcnt lgkmcnt(4)
	v_mfma_f32_32x32x16_bf16 v[66:81], v[180:183], v[184:187], v[66:81]
	ds_read_b128 v[168:171], v217 offset:192
	ds_read_b128 v[172:175], v217 offset:8896
	ds_read_b128 v[176:179], v217 offset:17600
	ds_read_b128 v[180:183], v217 offset:26304
	v_cvt_pk_bf16_f32 v184, v42, v43
	v_cvt_pk_bf16_f32 v185, v44, v45
	v_cvt_pk_bf16_f32 v186, v46, v47
	v_cvt_pk_bf16_f32 v187, v48, v49
	s_waitcnt lgkmcnt(7)
	s_nop 0
	v_mfma_f32_32x32x16_bf16 v[98:113], v[146:149], v[184:187], v[98:113]
	s_waitcnt lgkmcnt(6)
	v_mfma_f32_32x32x16_bf16 v[114:129], v[150:153], v[184:187], v[114:129]
	s_waitcnt lgkmcnt(5)
	v_mfma_f32_32x32x16_bf16 v[82:97], v[156:159], v[184:187], v[82:97]
	s_waitcnt lgkmcnt(4)
	v_mfma_f32_32x32x16_bf16 v[66:81], v[164:167], v[184:187], v[66:81]
	ds_read_b128 v[146:149], v217 offset:224
	ds_read_b128 v[150:153], v217 offset:8928
	ds_read_b128 v[156:159], v217 offset:17632
	ds_read_b128 v[164:167], v217 offset:26336
	v_cvt_pk_bf16_f32 v184, v2, v3
	v_cvt_pk_bf16_f32 v185, v4, v5
	v_cvt_pk_bf16_f32 v186, v6, v7
	v_cvt_pk_bf16_f32 v187, v8, v9
	s_waitcnt lgkmcnt(7)
	s_nop 0
	v_mfma_f32_32x32x16_bf16 v[98:113], v[168:171], v[184:187], v[98:113]
	s_waitcnt lgkmcnt(6)
	v_mfma_f32_32x32x16_bf16 v[114:129], v[172:175], v[184:187], v[114:129]
	s_waitcnt lgkmcnt(5)
	v_mfma_f32_32x32x16_bf16 v[82:97], v[176:179], v[184:187], v[82:97]
	s_waitcnt lgkmcnt(4)
	v_mfma_f32_32x32x16_bf16 v[66:81], v[180:183], v[184:187], v[66:81]
	v_cvt_pk_bf16_f32 v168, v10, v11
	v_cvt_pk_bf16_f32 v169, v12, v13
	v_cvt_pk_bf16_f32 v170, v14, v15
	v_cvt_pk_bf16_f32 v171, v16, v17
	s_waitcnt lgkmcnt(2)
	s_nop 0
	v_mfma_f32_32x32x16_bf16 v[114:129], v[150:153], v[168:171], v[114:129]
	s_waitcnt lgkmcnt(1)
	v_mfma_f32_32x32x16_bf16 v[82:97], v[156:159], v[168:171], v[82:97]
	s_waitcnt lgkmcnt(0)
	v_mfma_f32_32x32x16_bf16 v[66:81], v[164:167], v[168:171], v[66:81]
	ds_read_b128 v[164:167], v216 offset:34816
	ds_read_b128 v[172:175], v216 offset:34848
	ds_read_b128 v[176:179], v216 offset:34880
	ds_read_b128 v[180:183], v216 offset:34912
	ds_read_b128 v[184:187], v216 offset:39424
	ds_read_b128 v[188:191], v216 offset:39456
	ds_read_b128 v[224:227], v216 offset:39488
	ds_read_b128 v[228:231], v216 offset:39520
	v_mfma_f32_32x32x16_bf16 v[98:113], v[146:149], v[168:171], v[98:113]
	global_load_dwordx4 v[146:149], v[154:155], off offset:16
	global_load_dwordx4 v[150:153], v[154:155], off
	global_load_dwordx4 v[158:161], v[154:155], off offset:2064
	s_nop 0
	global_load_dwordx4 v[154:157], v[154:155], off offset:2048
	s_waitcnt vmcnt(7)
	v_lshlrev_b32_e32 v168, 16, v145
	v_and_b32_e32 v169, 0xffff0000, v145
	v_sub_f32_e32 v168, v168, v128
	v_sub_f32_e32 v169, v169, v129
	v_lshlrev_b32_e32 v128, 16, v144
	v_and_b32_e32 v129, 0xffff0000, v144
	v_sub_f32_e32 v128, v128, v126
	v_sub_f32_e32 v129, v129, v127
	v_lshlrev_b32_e32 v126, 16, v143
	v_and_b32_e32 v127, 0xffff0000, v143
	v_sub_f32_e32 v144, v126, v124
	v_sub_f32_e32 v145, v127, v125
	v_lshlrev_b32_e32 v124, 16, v142
	v_and_b32_e32 v125, 0xffff0000, v142
	v_sub_f32_e32 v126, v124, v122
	v_sub_f32_e32 v127, v125, v123
	s_waitcnt vmcnt(6)
	v_lshlrev_b32_e32 v122, 16, v141
	v_and_b32_e32 v123, 0xffff0000, v141
	v_sub_f32_e32 v120, v122, v120
	v_sub_f32_e32 v121, v123, v121
	v_lshlrev_b32_e32 v122, 16, v140
	v_and_b32_e32 v123, 0xffff0000, v140
	v_sub_f32_e32 v118, v122, v118
	v_sub_f32_e32 v119, v123, v119
	v_lshlrev_b32_e32 v122, 16, v139
	v_and_b32_e32 v123, 0xffff0000, v139
	v_sub_f32_e32 v116, v122, v116
	v_sub_f32_e32 v117, v123, v117
	v_lshlrev_b32_e32 v122, 16, v138
	v_and_b32_e32 v123, 0xffff0000, v138
	v_sub_f32_e32 v114, v122, v114
	v_sub_f32_e32 v115, v123, v115
	v_lshlrev_b32_e32 v122, 16, v134
	v_and_b32_e32 v123, 0xffff0000, v134
	v_sub_f32_e32 v98, v122, v98
	v_sub_f32_e32 v99, v123, v99
	v_lshlrev_b32_e32 v122, 16, v135
	v_and_b32_e32 v123, 0xffff0000, v135
	v_sub_f32_e32 v100, v122, v100
	v_sub_f32_e32 v101, v123, v101
	v_lshlrev_b32_e32 v122, 16, v136
	v_and_b32_e32 v123, 0xffff0000, v136
	v_sub_f32_e32 v102, v122, v102
	v_sub_f32_e32 v103, v123, v103
	v_lshlrev_b32_e32 v122, 16, v137
	v_and_b32_e32 v123, 0xffff0000, v137
	v_sub_f32_e32 v104, v122, v104
	v_sub_f32_e32 v105, v123, v105
	v_lshlrev_b32_e32 v122, 16, v130
	v_and_b32_e32 v123, 0xffff0000, v130
	v_sub_f32_e32 v106, v122, v106
	v_sub_f32_e32 v107, v123, v107
	v_lshlrev_b32_e32 v122, 16, v131
	v_and_b32_e32 v123, 0xffff0000, v131
	v_sub_f32_e32 v108, v122, v108
	v_sub_f32_e32 v109, v123, v109
	v_lshlrev_b32_e32 v122, 16, v132
	v_and_b32_e32 v123, 0xffff0000, v132
	v_sub_f32_e32 v110, v122, v110
	v_sub_f32_e32 v111, v123, v111
	v_lshlrev_b32_e32 v122, 16, v133
	v_and_b32_e32 v123, 0xffff0000, v133
	v_sub_f32_e32 v112, v122, v112
	v_sub_f32_e32 v113, v123, v113
	v_cvt_pk_bf16_f32 v98, v98, v99
	v_cvt_pk_bf16_f32 v99, v100, v101
	v_cvt_pk_bf16_f32 v100, v102, v103
	v_cvt_pk_bf16_f32 v101, v104, v105
	v_cvt_pk_bf16_f32 v102, v106, v107
	v_cvt_pk_bf16_f32 v103, v108, v109
	v_cvt_pk_bf16_f32 v104, v110, v111
	v_cvt_pk_bf16_f32 v105, v112, v113
	v_cvt_pk_bf16_f32 v106, v114, v115
	v_cvt_pk_bf16_f32 v107, v116, v117
	v_cvt_pk_bf16_f32 v108, v118, v119
	v_cvt_pk_bf16_f32 v109, v120, v121
	ds_read_b128 v[110:113], v218 offset:53248
	ds_read_b128 v[114:117], v218 offset:53280
	ds_read_b128 v[118:121], v218 offset:53312
	ds_read_b128 v[122:125], v218 offset:53344
	v_cvt_pk_bf16_f32 v126, v126, v127
	v_cvt_pk_bf16_f32 v127, v144, v145
	v_cvt_pk_bf16_f32 v128, v128, v129
	v_cvt_pk_bf16_f32 v129, v168, v169
	s_waitcnt vmcnt(5)
; DI unsigned pk2(float lo, float hi) { f32x2 v = {lo, hi}; return __builtin_bit_cast(unsigned, __builtin_convertvector(v, bf16v2)); }
; #define MFMA32(a, b, c) __builtin_amdgcn_mfma_f32_32x32x16_bf16((a), (b), (c), 0, 0, 0)
; DI void chain_step(f32x16 (&Sacc)[4], u32x4 (&uv)[4], const LAS unsigned char* buf, float gl, const bf16* uv_next, bf16* oraw, int r, int h2) {
;     ...
; #pragma unroll
;     for (int d = 0; d < 2; ++d) {
; #pragma unroll
;         for (int i = 0; i < 16; ++i) Sacc[d][i] *= gl;
; #pragma unroll
;         for (int k2 = 0; k2 < 4; ++k2) Sacc[d] = MFMA32(fk[d][k2], Uf[k2], Sacc[d]); }
; #pragma unroll
;     for (int d = 0; d < 2; ++d)
; #pragma unroll
;         for (int k2 = 0; k2 < 4; ++k2) fk[d][k2] = FR(KGTl, TLD, 2 + d, k2);
;     __builtin_amdgcn_sched_barrier(0);
; #pragma unroll
;     for (int k2 = 0; k2 < 4; ++k2) accO[0] = MFMA32(fp[k2], Uf[k2], accO[0]);
; #pragma unroll
;     for (int k2 = 0; k2 < 4; ++k2) fp[k2] = FR(PMl, TLD, 1, k2);
;     __builtin_amdgcn_sched_barrier(0);
; #pragma unroll
;     for (int d = 0; d < 2; ++d) {
; #pragma unroll
;         for (int i = 0; i < 16; ++i) Sacc[2 + d][i] *= gl;
; #pragma unroll
;         for (int k2 = 0; k2 < 4; ++k2) Sacc[2 + d] = MFMA32(fk[d][k2], Uf[k2], Sacc[2 + d]); }
; #pragma unroll
;     for (int k2 = 0; k2 < 4; ++k2) accO[1] = MFMA32(fp[k2], Uf[k2], accO[1]);
; #pragma unroll
;     for (int ti = 0; ti < 2; ++ti) { u32x4 w0, w1;
; #pragma unroll
;         for (int j = 0; j < 4; ++j) { w0[j] = pk2(accO[ti][2 * j], accO[ti][2 * j + 1]); w1[j] = pk2(accO[ti][8 + 2 * j], accO[ti][8 + 2 * j + 1]); }
;         *(u32x4*)(oraw + (size_t)(ti * 64) * 16) = w0; *(u32x4*)(oraw + (size_t)(ti * 64) * 16 + 8) = w1; }
	v_mul_f32_e32 v32, v202, v32
	v_mul_f32_e32 v33, v202, v33
	v_mul_f32_e32 v30, v202, v30
	v_mul_f32_e32 v31, v202, v31
	v_mul_f32_e32 v28, v202, v28
	v_mul_f32_e32 v29, v202, v29
	v_mul_f32_e32 v26, v202, v26
	v_mul_f32_e32 v27, v202, v27
	v_mul_f32_e32 v24, v202, v24
	v_mul_f32_e32 v25, v202, v25
	v_mul_f32_e32 v22, v202, v22
	v_mul_f32_e32 v23, v202, v23
	v_mul_f32_e32 v20, v202, v20
	v_mul_f32_e32 v21, v202, v21
	v_mul_f32_e32 v18, v202, v18
	v_mul_f32_e32 v19, v202, v19
	v_mul_f32_e32 v64, v202, v64
	v_mul_f32_e32 v65, v202, v65
	v_mul_f32_e32 v62, v202, v62
	v_mul_f32_e32 v63, v202, v63
	v_mul_f32_e32 v60, v202, v60
	v_mul_f32_e32 v61, v202, v61
	v_mul_f32_e32 v58, v202, v58
	v_mul_f32_e32 v59, v202, v59
	v_mul_f32_e32 v56, v202, v56
	v_mul_f32_e32 v57, v202, v57
	v_mul_f32_e32 v54, v202, v54
	v_mul_f32_e32 v55, v202, v55
	v_mul_f32_e32 v52, v202, v52
	v_mul_f32_e32 v53, v202, v53
	v_mul_f32_e32 v50, v202, v50
	v_mul_f32_e32 v51, v202, v51
	s_waitcnt lgkmcnt(11)
	v_mfma_f32_32x32x16_bf16 v[18:33], v[164:167], v[98:101], v[18:33]
	s_waitcnt lgkmcnt(7)
	v_mfma_f32_32x32x16_bf16 v[50:65], v[184:187], v[98:101], v[50:65]
	v_mfma_f32_32x32x16_bf16 v[18:33], v[172:175], v[102:105], v[18:33]
	s_waitcnt lgkmcnt(6)
	v_mfma_f32_32x32x16_bf16 v[50:65], v[188:191], v[102:105], v[50:65]
	v_mfma_f32_32x32x16_bf16 v[18:33], v[176:179], v[106:109], v[18:33]
	ds_read_b128 v[130:133], v216 offset:44032
	ds_read_b128 v[134:137], v216 offset:44064
	ds_read_b128 v[138:141], v216 offset:44096
	ds_read_b128 v[142:145], v216 offset:44128
	ds_read_b128 v[164:167], v216 offset:48640
	ds_read_b128 v[168:171], v216 offset:48672
	ds_read_b128 v[172:175], v216 offset:48704
	ds_read_b128 v[176:179], v216 offset:48736
	s_waitcnt lgkmcnt(13)
	v_mfma_f32_32x32x16_bf16 v[50:65], v[224:227], v[106:109], v[50:65]
	v_mfma_f32_32x32x16_bf16 v[18:33], v[180:183], v[126:129], v[18:33]
	s_waitcnt lgkmcnt(12)
	v_mfma_f32_32x32x16_bf16 v[50:65], v[228:231], v[126:129], v[50:65]
	s_waitcnt lgkmcnt(11)
	v_mfma_f32_32x32x16_bf16 v[82:97], v[110:113], v[98:101], v[82:97]
	s_waitcnt lgkmcnt(10)
	v_mfma_f32_32x32x16_bf16 v[82:97], v[114:117], v[102:105], v[82:97]
	s_waitcnt lgkmcnt(9)
	v_mfma_f32_32x32x16_bf16 v[82:97], v[118:121], v[106:109], v[82:97]
	s_waitcnt lgkmcnt(8)
	v_mfma_f32_32x32x16_bf16 v[82:97], v[122:125], v[126:129], v[82:97]
	ds_read_b128 v[110:113], v218 offset:57856
	ds_read_b128 v[114:117], v218 offset:57888
	ds_read_b128 v[118:121], v218 offset:57920
	ds_read_b128 v[122:125], v218 offset:57952
	s_waitcnt lgkmcnt(3)
	v_mfma_f32_32x32x16_bf16 v[66:81], v[110:113], v[98:101], v[66:81]
	v_mul_f32_e64 v48, v202, v48
	v_mul_f32_e64 v49, v202, v49
	v_mul_f32_e64 v46, v202, v46
	v_mul_f32_e64 v47, v202, v47
	v_mul_f32_e64 v44, v202, v44
	v_mul_f32_e64 v45, v202, v45
	v_mul_f32_e32 v42, v202, v42
	v_mul_f32_e32 v43, v202, v43
	v_mul_f32_e32 v40, v202, v40
	v_mul_f32_e32 v41, v202, v41
	v_mul_f32_e32 v38, v202, v38
	v_mul_f32_e32 v39, v202, v39
	v_mul_f32_e32 v36, v202, v36
	v_mul_f32_e32 v37, v202, v37
	v_mul_f32_e32 v34, v202, v34
	v_mul_f32_e32 v35, v202, v35
	v_mul_f32_e32 v16, v202, v16
	v_mul_f32_e32 v17, v202, v17
	v_mul_f32_e32 v14, v202, v14
	v_mul_f32_e32 v15, v202, v15
	v_mul_f32_e32 v12, v202, v12
	v_mul_f32_e32 v13, v202, v13
	v_mul_f32_e32 v10, v202, v10
	v_mul_f32_e32 v11, v202, v11
	v_mul_f32_e32 v8, v202, v8
	v_mul_f32_e32 v9, v202, v9
	v_mul_f32_e32 v6, v202, v6
	v_mul_f32_e32 v7, v202, v7
	v_mul_f32_e32 v4, v202, v4
	v_mul_f32_e32 v5, v202, v5
	v_mul_f32_e32 v2, v202, v2
	v_mul_f32_e32 v3, v202, v3
	v_mfma_f32_32x32x16_bf16 v[34:49], v[130:133], v[98:101], v[34:49]
	v_cvt_pk_bf16_f32 v82, v82, v83
	v_cvt_pk_bf16_f32 v83, v84, v85
	v_cvt_pk_bf16_f32 v84, v86, v87
	v_cvt_pk_bf16_f32 v85, v88, v89
	v_cvt_pk_bf16_f32 v90, v90, v91
	v_cvt_pk_bf16_f32 v91, v92, v93
	v_cvt_pk_bf16_f32 v92, v94, v95
	v_mfma_f32_32x32x16_bf16 v[2:17], v[164:167], v[98:101], v[2:17]
	v_cvt_pk_bf16_f32 v93, v96, v97
	global_store_dwordx4 v[162:163], v[82:85], off
	global_store_dwordx4 v[162:163], v[90:93], off offset:16
	s_cmp_lt_u32 s80, 62
	s_cselect_b64 s[56:57], -1, 0
	s_cmp_gt_u32 s80, 61
	v_mov_b32_e32 v202, 0
	s_waitcnt lgkmcnt(2)
	v_mfma_f32_32x32x16_bf16 v[66:81], v[114:117], v[102:105], v[66:81]
	v_mfma_f32_32x32x16_bf16 v[34:49], v[134:137], v[102:105], v[34:49]
	v_mfma_f32_32x32x16_bf16 v[2:17], v[168:171], v[102:105], v[2:17]
	s_waitcnt lgkmcnt(1)
	v_mfma_f32_32x32x16_bf16 v[66:81], v[118:121], v[106:109], v[66:81]
	v_mfma_f32_32x32x16_bf16 v[34:49], v[138:141], v[106:109], v[34:49]
	v_mfma_f32_32x32x16_bf16 v[2:17], v[172:175], v[106:109], v[2:17]
	s_waitcnt lgkmcnt(0)
	v_mfma_f32_32x32x16_bf16 v[66:81], v[122:125], v[126:129], v[66:81]
	v_mfma_f32_32x32x16_bf16 v[34:49], v[142:145], v[126:129], v[34:49]
	s_nop 10
	v_cvt_pk_bf16_f32 v66, v66, v67
	v_cvt_pk_bf16_f32 v74, v74, v75
	v_cvt_pk_bf16_f32 v67, v68, v69
	v_cvt_pk_bf16_f32 v75, v76, v77
	v_cvt_pk_bf16_f32 v68, v70, v71
	v_cvt_pk_bf16_f32 v76, v78, v79
	v_cvt_pk_bf16_f32 v69, v72, v73
	v_mfma_f32_32x32x16_bf16 v[2:17], v[176:179], v[126:129], v[2:17]
	v_cvt_pk_bf16_f32 v77, v80, v81
	global_store_dwordx4 v[162:163], v[66:69], off offset:2048
	global_store_dwordx4 v[162:163], v[74:77], off offset:2064
	s_waitcnt lgkmcnt(0)
	s_barrier
	s_cbranch_scc1 .LBB0_1776
	global_load_dword v202, v197, s[38:39]
